# phase H epilogue: the (ineffective) L2 warm-up touch of the next tile and its address arithmetic removed
# speedup vs baseline: 1.0003x; 1.0003x over previous
; DI uint2 pk4(float a, float b, float c, float d) { uint2 o; o.x = pk2(a, b); o.y = pk2(c, d); return o; }
; DI void phaseH(int wv0, PP p, unsigned char* smem) {
;     ...
;   for (int id = blockIdx.x; id < 128 * 16; id += gridDim.x) {
;     int pm, pn;
;     tile_map_n16(id, pm, pn);
;     const int brow = pm * 256, bcol = pn * 256;
;     const int tid = my_tid(wv0);
;     if (tid < 256) {
;       const float4* s = (const float4*)(SS1 + (size_t)(brow + tid) * 16);
;       const float4 a = s[0], b = s[1], c = s[2], d = s[3];
;       const float t = a.x + a.y + a.z + a.w + b.x + b.y + b.z + b.w + c.x + c.y + c.z + c.w + d.x + d.y + d.z + d.w;
;       sR[tid] = rsqrtf(t * (1.f / 1024.f) + 1e-6f);
;     }
;     f32x4 acc[2][2][4][2];
;     gemm256(wv0, acc, X1B + (size_t)brow * 1024, 1024, (const u16*)(p->ws + OFF_WUPT) + (size_t)bcol * 1024, 1024, 1024, smem);
;     epi256(wv0, acc, brow, bcol, [&](int ai, int bj, int m, int n, int row, int col0, f32x4& v) {
;       const float ri = sR[row - brow];
;       const float a0 = fmaxf(v[0] * ri, 0.f), a1 = fmaxf(v[1] * ri, 0.f), a2 = fmaxf(v[2] * ri, 0.f), a3 = fmaxf(v[3] * ri, 0.f);
;       *(uint2*)(ACT + (size_t)row * 4096 + col0) = pk4(a0 * a0, a1 * a1, a2 * a2, a3 * a3);
.LBB0_1133:
	s_load_dword s88, s[16:17], 0x0
	s_waitcnt lgkmcnt(0)
	s_add_i32 s88, s88, s67
	s_cmpk_lt_i32 s88, 0x800
	s_cbranch_scc0 .Lmy_hw_skip
	s_ashr_i32 s83, s88, 4
	s_and_b32 s83, s83, -16
	s_lshl_b32 s84, s88, 1
	s_and_b32 s84, s84, 12
	s_or_b32 s83, s83, s84
	s_bfe_u32 s84, s88, 0x20006
	s_or_b32 s83, s83, s84
	s_lshl_b32 s84, s83, 8
	s_mov_b32 s80, 1
	v_and_b32_e32 v184, 0xff, v142
	v_add_u32_e32 v184, s84, v184
	v_mov_b32_e32 v185, 0
	v_lshlrev_b64 v[184:185], 6, v[184:185]
	v_lshl_add_u64 v[184:185], s[8:9], 0, v[184:185]
	global_load_dwordx4 v[168:171], v[184:185], off
	global_load_dwordx4 v[172:175], v[184:185], off offset:16
	global_load_dwordx4 v[176:179], v[184:185], off offset:32
	global_load_dwordx4 v[180:183], v[184:185], off offset:48
.Lmy_hw_skip:
	v_and_b32_e32 v130, 15, v142
	v_bfe_u32 v131, v142, 4, 2
	v_add_u32_e32 v132, s51, v130
	v_lshlrev_b32_e32 v133, 2, v132
	v_add_u32_e32 v133, 0x21400, v133
	ds_read_b32 v200, v133 offset:0
	ds_read_b32 v202, v133 offset:64
	ds_read_b32 v204, v133 offset:128
	ds_read_b32 v206, v133 offset:192
	ds_read_b32 v208, v133 offset:512
	ds_read_b32 v210, v133 offset:576
	ds_read_b32 v212, v133 offset:640
	ds_read_b32 v214, v133 offset:704
	v_mul_u32_u24_e32 v134, 528, v132
	v_lshlrev_b32_e32 v135, 3, v131
	s_lshl_b32 s78, s57, 1
	v_add3_u32 v134, v134, v135, s78
	v_add_u32_e32 v134, 32, v134
	v_add_u32_e32 v136, 67584, v134
	s_waitcnt lgkmcnt(0)
	v_mul_f32_e32 v124, v124, v200
	v_mul_f32_e32 v125, v125, v200
	v_mul_f32_e32 v126, v126, v200
	v_mul_f32_e32 v127, v127, v200
	v_max_f32_e32 v124, 0, v124
	v_max_f32_e32 v125, 0, v125
	v_max_f32_e32 v126, 0, v126
	v_max_f32_e32 v127, 0, v127
	v_pk_mul_f32 v[124:125], v[124:125], v[124:125]
	v_pk_mul_f32 v[126:127], v[126:127], v[126:127]
	v_cvt_pk_bf16_f32 v124, v124, v125
	v_cvt_pk_bf16_f32 v125, v126, v127
	ds_write_b64 v134, v[124:125] offset:0
	v_mul_f32_e32 v120, v120, v200
	v_mul_f32_e32 v121, v121, v200
	v_mul_f32_e32 v122, v122, v200
	v_mul_f32_e32 v123, v123, v200
	v_max_f32_e32 v120, 0, v120
	v_max_f32_e32 v121, 0, v121
	v_max_f32_e32 v122, 0, v122
	v_max_f32_e32 v123, 0, v123
	v_pk_mul_f32 v[120:121], v[120:121], v[120:121]
	v_pk_mul_f32 v[122:123], v[122:123], v[122:123]
	v_cvt_pk_bf16_f32 v120, v120, v121
	v_cvt_pk_bf16_f32 v121, v122, v123
	ds_write_b64 v134, v[120:121] offset:32
	v_mul_f32_e32 v116, v116, v202
	v_mul_f32_e32 v117, v117, v202
	v_mul_f32_e32 v118, v118, v202
	v_mul_f32_e32 v119, v119, v202
	v_max_f32_e32 v116, 0, v116
	v_max_f32_e32 v117, 0, v117
	v_max_f32_e32 v118, 0, v118
	v_max_f32_e32 v119, 0, v119
	v_pk_mul_f32 v[116:117], v[116:117], v[116:117]
	v_pk_mul_f32 v[118:119], v[118:119], v[118:119]
	v_cvt_pk_bf16_f32 v116, v116, v117
	v_cvt_pk_bf16_f32 v117, v118, v119
	ds_write_b64 v134, v[116:117] offset:8448
	v_mul_f32_e32 v112, v112, v202
	v_mul_f32_e32 v113, v113, v202
	v_mul_f32_e32 v114, v114, v202
	v_mul_f32_e32 v115, v115, v202
	v_max_f32_e32 v112, 0, v112
	v_max_f32_e32 v113, 0, v113
	v_max_f32_e32 v114, 0, v114
	v_max_f32_e32 v115, 0, v115
	v_pk_mul_f32 v[112:113], v[112:113], v[112:113]
	v_pk_mul_f32 v[114:115], v[114:115], v[114:115]
	v_cvt_pk_bf16_f32 v112, v112, v113
	v_cvt_pk_bf16_f32 v113, v114, v115
	ds_write_b64 v134, v[112:113] offset:8480
	v_mul_f32_e32 v108, v108, v204
	v_mul_f32_e32 v109, v109, v204
	v_mul_f32_e32 v110, v110, v204
	v_mul_f32_e32 v111, v111, v204
	v_max_f32_e32 v108, 0, v108
	v_max_f32_e32 v109, 0, v109
	v_max_f32_e32 v110, 0, v110
	v_max_f32_e32 v111, 0, v111
	v_pk_mul_f32 v[108:109], v[108:109], v[108:109]
	v_pk_mul_f32 v[110:111], v[110:111], v[110:111]
	v_cvt_pk_bf16_f32 v108, v108, v109
	v_cvt_pk_bf16_f32 v109, v110, v111
	ds_write_b64 v134, v[108:109] offset:16896
	v_mul_f32_e32 v104, v104, v204
	v_mul_f32_e32 v105, v105, v204
	v_mul_f32_e32 v106, v106, v204
	v_mul_f32_e32 v107, v107, v204
	v_max_f32_e32 v104, 0, v104
	v_max_f32_e32 v105, 0, v105
	v_max_f32_e32 v106, 0, v106
	v_max_f32_e32 v107, 0, v107
	v_pk_mul_f32 v[104:105], v[104:105], v[104:105]
	v_pk_mul_f32 v[106:107], v[106:107], v[106:107]
	v_cvt_pk_bf16_f32 v104, v104, v105
	v_cvt_pk_bf16_f32 v105, v106, v107
	ds_write_b64 v134, v[104:105] offset:16928
	v_mul_f32_e32 v100, v100, v206
	v_mul_f32_e32 v101, v101, v206
	v_mul_f32_e32 v102, v102, v206
	v_mul_f32_e32 v103, v103, v206
	v_max_f32_e32 v100, 0, v100
	v_max_f32_e32 v101, 0, v101
	v_max_f32_e32 v102, 0, v102
	v_max_f32_e32 v103, 0, v103
	v_pk_mul_f32 v[100:101], v[100:101], v[100:101]
	v_pk_mul_f32 v[102:103], v[102:103], v[102:103]
	v_cvt_pk_bf16_f32 v100, v100, v101
	v_cvt_pk_bf16_f32 v101, v102, v103
	ds_write_b64 v134, v[100:101] offset:25344
	v_mul_f32_e32 v96, v96, v206
	v_mul_f32_e32 v97, v97, v206
	v_mul_f32_e32 v98, v98, v206
	v_mul_f32_e32 v99, v99, v206
	v_max_f32_e32 v96, 0, v96
	v_max_f32_e32 v97, 0, v97
	v_max_f32_e32 v98, 0, v98
	v_max_f32_e32 v99, 0, v99
	v_pk_mul_f32 v[96:97], v[96:97], v[96:97]
	v_pk_mul_f32 v[98:99], v[98:99], v[98:99]
	v_cvt_pk_bf16_f32 v96, v96, v97
	v_cvt_pk_bf16_f32 v97, v98, v99
	ds_write_b64 v134, v[96:97] offset:25376
	v_mul_f32_e32 v92, v92, v200
	v_mul_f32_e32 v93, v93, v200
	v_mul_f32_e32 v94, v94, v200
	v_mul_f32_e32 v95, v95, v200
	v_max_f32_e32 v92, 0, v92
	v_max_f32_e32 v93, 0, v93
	v_max_f32_e32 v94, 0, v94
	v_max_f32_e32 v95, 0, v95
	v_pk_mul_f32 v[92:93], v[92:93], v[92:93]
	v_pk_mul_f32 v[94:95], v[94:95], v[94:95]
	v_cvt_pk_bf16_f32 v92, v92, v93
	v_cvt_pk_bf16_f32 v93, v94, v95
	ds_write_b64 v134, v[92:93] offset:256
	v_mul_f32_e32 v88, v88, v200
	v_mul_f32_e32 v89, v89, v200
	v_mul_f32_e32 v90, v90, v200
	v_mul_f32_e32 v91, v91, v200
	v_max_f32_e32 v88, 0, v88
	v_max_f32_e32 v89, 0, v89
; DI uint2 pk4(float a, float b, float c, float d) { uint2 o; o.x = pk2(a, b); o.y = pk2(c, d); return o; }
; DI void phaseH(int wv0, PP p, unsigned char* smem) {
;     ...
;     epi256(wv0, acc, brow, bcol, [&](int ai, int bj, int m, int n, int row, int col0, f32x4& v) {
;       const float ri = sR[row - brow];
;       const float a0 = fmaxf(v[0] * ri, 0.f), a1 = fmaxf(v[1] * ri, 0.f), a2 = fmaxf(v[2] * ri, 0.f), a3 = fmaxf(v[3] * ri, 0.f);
;       *(uint2*)(ACT + (size_t)row * 4096 + col0) = pk4(a0 * a0, a1 * a1, a2 * a2, a3 * a3);
	v_max_f32_e32 v90, 0, v90
	v_max_f32_e32 v91, 0, v91
	v_pk_mul_f32 v[88:89], v[88:89], v[88:89]
	v_pk_mul_f32 v[90:91], v[90:91], v[90:91]
	v_cvt_pk_bf16_f32 v88, v88, v89
	v_cvt_pk_bf16_f32 v89, v90, v91
	ds_write_b64 v134, v[88:89] offset:288
	v_mul_f32_e32 v84, v84, v202
	v_mul_f32_e32 v85, v85, v202
	v_mul_f32_e32 v86, v86, v202
	v_mul_f32_e32 v87, v87, v202
	v_max_f32_e32 v84, 0, v84
	v_max_f32_e32 v85, 0, v85
	v_max_f32_e32 v86, 0, v86
	v_max_f32_e32 v87, 0, v87
	v_pk_mul_f32 v[84:85], v[84:85], v[84:85]
	v_pk_mul_f32 v[86:87], v[86:87], v[86:87]
	v_cvt_pk_bf16_f32 v84, v84, v85
	v_cvt_pk_bf16_f32 v85, v86, v87
	ds_write_b64 v134, v[84:85] offset:8704
	v_mul_f32_e32 v80, v80, v202
	v_mul_f32_e32 v81, v81, v202
	v_mul_f32_e32 v82, v82, v202
	v_mul_f32_e32 v83, v83, v202
	v_max_f32_e32 v80, 0, v80
	v_max_f32_e32 v81, 0, v81
	v_max_f32_e32 v82, 0, v82
	v_max_f32_e32 v83, 0, v83
	v_pk_mul_f32 v[80:81], v[80:81], v[80:81]
	v_pk_mul_f32 v[82:83], v[82:83], v[82:83]
	v_cvt_pk_bf16_f32 v80, v80, v81
	v_cvt_pk_bf16_f32 v81, v82, v83
	ds_write_b64 v134, v[80:81] offset:8736
	v_mul_f32_e32 v76, v76, v204
	v_mul_f32_e32 v77, v77, v204
	v_mul_f32_e32 v78, v78, v204
	v_mul_f32_e32 v79, v79, v204
	v_max_f32_e32 v76, 0, v76
	v_max_f32_e32 v77, 0, v77
	v_max_f32_e32 v78, 0, v78
	v_max_f32_e32 v79, 0, v79
	v_pk_mul_f32 v[76:77], v[76:77], v[76:77]
	v_pk_mul_f32 v[78:79], v[78:79], v[78:79]
	v_cvt_pk_bf16_f32 v76, v76, v77
	v_cvt_pk_bf16_f32 v77, v78, v79
	ds_write_b64 v134, v[76:77] offset:17152
	v_mul_f32_e32 v72, v72, v204
	v_mul_f32_e32 v73, v73, v204
	v_mul_f32_e32 v74, v74, v204
	v_mul_f32_e32 v75, v75, v204
	v_max_f32_e32 v72, 0, v72
	v_max_f32_e32 v73, 0, v73
	v_max_f32_e32 v74, 0, v74
	v_max_f32_e32 v75, 0, v75
	v_pk_mul_f32 v[72:73], v[72:73], v[72:73]
	v_pk_mul_f32 v[74:75], v[74:75], v[74:75]
	v_cvt_pk_bf16_f32 v72, v72, v73
	v_cvt_pk_bf16_f32 v73, v74, v75
	ds_write_b64 v134, v[72:73] offset:17184
	v_mul_f32_e32 v68, v68, v206
	v_mul_f32_e32 v69, v69, v206
	v_mul_f32_e32 v70, v70, v206
	v_mul_f32_e32 v71, v71, v206
	v_max_f32_e32 v68, 0, v68
	v_max_f32_e32 v69, 0, v69
	v_max_f32_e32 v70, 0, v70
	v_max_f32_e32 v71, 0, v71
	v_pk_mul_f32 v[68:69], v[68:69], v[68:69]
	v_pk_mul_f32 v[70:71], v[70:71], v[70:71]
	v_cvt_pk_bf16_f32 v68, v68, v69
	v_cvt_pk_bf16_f32 v69, v70, v71
	ds_write_b64 v134, v[68:69] offset:25600
	v_mul_f32_e32 v64, v64, v206
	v_mul_f32_e32 v65, v65, v206
	v_mul_f32_e32 v66, v66, v206
	v_mul_f32_e32 v67, v67, v206
	v_max_f32_e32 v64, 0, v64
	v_max_f32_e32 v65, 0, v65
	v_max_f32_e32 v66, 0, v66
	v_max_f32_e32 v67, 0, v67
	v_pk_mul_f32 v[64:65], v[64:65], v[64:65]
	v_pk_mul_f32 v[66:67], v[66:67], v[66:67]
	v_cvt_pk_bf16_f32 v64, v64, v65
	v_cvt_pk_bf16_f32 v65, v66, v67
	ds_write_b64 v134, v[64:65] offset:25632
	v_mul_f32_e32 v60, v60, v208
	v_mul_f32_e32 v61, v61, v208
	v_mul_f32_e32 v62, v62, v208
	v_mul_f32_e32 v63, v63, v208
	v_max_f32_e32 v60, 0, v60
	v_max_f32_e32 v61, 0, v61
	v_max_f32_e32 v62, 0, v62
	v_max_f32_e32 v63, 0, v63
	v_pk_mul_f32 v[60:61], v[60:61], v[60:61]
	v_pk_mul_f32 v[62:63], v[62:63], v[62:63]
	v_cvt_pk_bf16_f32 v60, v60, v61
	v_cvt_pk_bf16_f32 v61, v62, v63
	ds_write_b64 v136, v[60:61] offset:0
	v_mul_f32_e32 v56, v56, v208
	v_mul_f32_e32 v57, v57, v208
	v_mul_f32_e32 v58, v58, v208
	v_mul_f32_e32 v59, v59, v208
	v_max_f32_e32 v56, 0, v56
	v_max_f32_e32 v57, 0, v57
	v_max_f32_e32 v58, 0, v58
	v_max_f32_e32 v59, 0, v59
	v_pk_mul_f32 v[56:57], v[56:57], v[56:57]
	v_pk_mul_f32 v[58:59], v[58:59], v[58:59]
	v_cvt_pk_bf16_f32 v56, v56, v57
	v_cvt_pk_bf16_f32 v57, v58, v59
	ds_write_b64 v136, v[56:57] offset:32
	v_mul_f32_e32 v52, v52, v210
	v_mul_f32_e32 v53, v53, v210
	v_mul_f32_e32 v54, v54, v210
	v_mul_f32_e32 v55, v55, v210
	v_max_f32_e32 v52, 0, v52
	v_max_f32_e32 v53, 0, v53
	v_max_f32_e32 v54, 0, v54
	v_max_f32_e32 v55, 0, v55
	v_pk_mul_f32 v[52:53], v[52:53], v[52:53]
	v_pk_mul_f32 v[54:55], v[54:55], v[54:55]
	v_cvt_pk_bf16_f32 v52, v52, v53
	v_cvt_pk_bf16_f32 v53, v54, v55
	ds_write_b64 v136, v[52:53] offset:8448
	v_mul_f32_e32 v48, v48, v210
	v_mul_f32_e32 v49, v49, v210
	v_mul_f32_e32 v50, v50, v210
	v_mul_f32_e32 v51, v51, v210
	v_max_f32_e32 v48, 0, v48
	v_max_f32_e32 v49, 0, v49
	v_max_f32_e32 v50, 0, v50
	v_max_f32_e32 v51, 0, v51
	v_pk_mul_f32 v[48:49], v[48:49], v[48:49]
	v_pk_mul_f32 v[50:51], v[50:51], v[50:51]
	v_cvt_pk_bf16_f32 v48, v48, v49
	v_cvt_pk_bf16_f32 v49, v50, v51
	ds_write_b64 v136, v[48:49] offset:8480
	v_mul_f32_e32 v44, v44, v212
	v_mul_f32_e32 v45, v45, v212
	v_mul_f32_e32 v46, v46, v212
	v_mul_f32_e32 v47, v47, v212
	v_max_f32_e32 v44, 0, v44
	v_max_f32_e32 v45, 0, v45
	v_max_f32_e32 v46, 0, v46
	v_max_f32_e32 v47, 0, v47
	v_pk_mul_f32 v[44:45], v[44:45], v[44:45]
	v_pk_mul_f32 v[46:47], v[46:47], v[46:47]
	v_cvt_pk_bf16_f32 v44, v44, v45
	v_cvt_pk_bf16_f32 v45, v46, v47
	ds_write_b64 v136, v[44:45] offset:16896
	v_mul_f32_e32 v40, v40, v212
	v_mul_f32_e32 v41, v41, v212
	v_mul_f32_e32 v42, v42, v212
	v_mul_f32_e32 v43, v43, v212
	v_max_f32_e32 v40, 0, v40
	v_max_f32_e32 v41, 0, v41
	v_max_f32_e32 v42, 0, v42
	v_max_f32_e32 v43, 0, v43
	v_pk_mul_f32 v[40:41], v[40:41], v[40:41]
	v_pk_mul_f32 v[42:43], v[42:43], v[42:43]
	v_cvt_pk_bf16_f32 v40, v40, v41
	v_cvt_pk_bf16_f32 v41, v42, v43
	ds_write_b64 v136, v[40:41] offset:16928
	v_mul_f32_e32 v36, v36, v214
	v_mul_f32_e32 v37, v37, v214
	v_mul_f32_e32 v38, v38, v214
	v_mul_f32_e32 v39, v39, v214
	v_max_f32_e32 v36, 0, v36
	v_max_f32_e32 v37, 0, v37
	v_max_f32_e32 v38, 0, v38
	v_max_f32_e32 v39, 0, v39
	v_pk_mul_f32 v[36:37], v[36:37], v[36:37]
	v_pk_mul_f32 v[38:39], v[38:39], v[38:39]
	v_cvt_pk_bf16_f32 v36, v36, v37
; DI uint2 pk4(float a, float b, float c, float d) { uint2 o; o.x = pk2(a, b); o.y = pk2(c, d); return o; }
; DI void phaseH(int wv0, PP p, unsigned char* smem) {
;     ...
;     const int tid = my_tid(wv0);
;     if (tid < 256) {
;       const float4* s = (const float4*)(SS1 + (size_t)(brow + tid) * 16);
;       const float4 a = s[0], b = s[1], c = s[2], d = s[3];
;       const float t = a.x + a.y + a.z + a.w + b.x + b.y + b.z + b.w + c.x + c.y + c.z + c.w + d.x + d.y + d.z + d.w;
;       sR[tid] = rsqrtf(t * (1.f / 1024.f) + 1e-6f);
;     }
;     f32x4 acc[2][2][4][2];
;     gemm256(wv0, acc, X1B + (size_t)brow * 1024, 1024, (const u16*)(p->ws + OFF_WUPT) + (size_t)bcol * 1024, 1024, 1024, smem);
;     epi256(wv0, acc, brow, bcol, [&](int ai, int bj, int m, int n, int row, int col0, f32x4& v) {
;       const float ri = sR[row - brow];
;       const float a0 = fmaxf(v[0] * ri, 0.f), a1 = fmaxf(v[1] * ri, 0.f), a2 = fmaxf(v[2] * ri, 0.f), a3 = fmaxf(v[3] * ri, 0.f);
;       *(uint2*)(ACT + (size_t)row * 4096 + col0) = pk4(a0 * a0, a1 * a1, a2 * a2, a3 * a3);
	v_cvt_pk_bf16_f32 v37, v38, v39
	ds_write_b64 v136, v[36:37] offset:25344
	v_mul_f32_e32 v32, v32, v214
	v_mul_f32_e32 v33, v33, v214
	v_mul_f32_e32 v34, v34, v214
	v_mul_f32_e32 v35, v35, v214
	v_max_f32_e32 v32, 0, v32
	v_max_f32_e32 v33, 0, v33
	v_max_f32_e32 v34, 0, v34
	v_max_f32_e32 v35, 0, v35
	v_pk_mul_f32 v[32:33], v[32:33], v[32:33]
	v_pk_mul_f32 v[34:35], v[34:35], v[34:35]
	v_cvt_pk_bf16_f32 v32, v32, v33
	v_cvt_pk_bf16_f32 v33, v34, v35
	ds_write_b64 v136, v[32:33] offset:25376
	v_mul_f32_e32 v28, v28, v208
	v_mul_f32_e32 v29, v29, v208
	v_mul_f32_e32 v30, v30, v208
	v_mul_f32_e32 v31, v31, v208
	v_max_f32_e32 v28, 0, v28
	v_max_f32_e32 v29, 0, v29
	v_max_f32_e32 v30, 0, v30
	v_max_f32_e32 v31, 0, v31
	v_pk_mul_f32 v[28:29], v[28:29], v[28:29]
	v_pk_mul_f32 v[30:31], v[30:31], v[30:31]
	v_cvt_pk_bf16_f32 v28, v28, v29
	v_cvt_pk_bf16_f32 v29, v30, v31
	ds_write_b64 v136, v[28:29] offset:256
	v_mul_f32_e32 v24, v24, v208
	v_mul_f32_e32 v25, v25, v208
	v_mul_f32_e32 v26, v26, v208
	v_mul_f32_e32 v27, v27, v208
	v_max_f32_e32 v24, 0, v24
	v_max_f32_e32 v25, 0, v25
	v_max_f32_e32 v26, 0, v26
	v_max_f32_e32 v27, 0, v27
	v_pk_mul_f32 v[24:25], v[24:25], v[24:25]
	v_pk_mul_f32 v[26:27], v[26:27], v[26:27]
	v_cvt_pk_bf16_f32 v24, v24, v25
	v_cvt_pk_bf16_f32 v25, v26, v27
	ds_write_b64 v136, v[24:25] offset:288
	v_mul_f32_e32 v20, v20, v210
	v_mul_f32_e32 v21, v21, v210
	v_mul_f32_e32 v22, v22, v210
	v_mul_f32_e32 v23, v23, v210
	v_max_f32_e32 v20, 0, v20
	v_max_f32_e32 v21, 0, v21
	v_max_f32_e32 v22, 0, v22
	v_max_f32_e32 v23, 0, v23
	v_pk_mul_f32 v[20:21], v[20:21], v[20:21]
	v_pk_mul_f32 v[22:23], v[22:23], v[22:23]
	v_cvt_pk_bf16_f32 v20, v20, v21
	v_cvt_pk_bf16_f32 v21, v22, v23
	ds_write_b64 v136, v[20:21] offset:8704
	v_mul_f32_e32 v16, v16, v210
	v_mul_f32_e32 v17, v17, v210
	v_mul_f32_e32 v18, v18, v210
	v_mul_f32_e32 v19, v19, v210
	v_max_f32_e32 v16, 0, v16
	v_max_f32_e32 v17, 0, v17
	v_max_f32_e32 v18, 0, v18
	v_max_f32_e32 v19, 0, v19
	v_pk_mul_f32 v[16:17], v[16:17], v[16:17]
	v_pk_mul_f32 v[18:19], v[18:19], v[18:19]
	v_cvt_pk_bf16_f32 v16, v16, v17
	v_cvt_pk_bf16_f32 v17, v18, v19
	ds_write_b64 v136, v[16:17] offset:8736
	v_mul_f32_e32 v12, v12, v212
	v_mul_f32_e32 v13, v13, v212
	v_mul_f32_e32 v14, v14, v212
	v_mul_f32_e32 v15, v15, v212
	v_max_f32_e32 v12, 0, v12
	v_max_f32_e32 v13, 0, v13
	v_max_f32_e32 v14, 0, v14
	v_max_f32_e32 v15, 0, v15
	v_pk_mul_f32 v[12:13], v[12:13], v[12:13]
	v_pk_mul_f32 v[14:15], v[14:15], v[14:15]
	v_cvt_pk_bf16_f32 v12, v12, v13
	v_cvt_pk_bf16_f32 v13, v14, v15
	ds_write_b64 v136, v[12:13] offset:17152
	v_mul_f32_e32 v8, v8, v212
	v_mul_f32_e32 v9, v9, v212
	v_mul_f32_e32 v10, v10, v212
	v_mul_f32_e32 v11, v11, v212
	v_max_f32_e32 v8, 0, v8
	v_max_f32_e32 v9, 0, v9
	v_max_f32_e32 v10, 0, v10
	v_max_f32_e32 v11, 0, v11
	v_pk_mul_f32 v[8:9], v[8:9], v[8:9]
	v_pk_mul_f32 v[10:11], v[10:11], v[10:11]
	v_cvt_pk_bf16_f32 v8, v8, v9
	v_cvt_pk_bf16_f32 v9, v10, v11
	ds_write_b64 v136, v[8:9] offset:17184
	v_mul_f32_e32 v4, v4, v214
	v_mul_f32_e32 v5, v5, v214
	v_mul_f32_e32 v6, v6, v214
	v_mul_f32_e32 v7, v7, v214
	v_max_f32_e32 v4, 0, v4
	v_max_f32_e32 v5, 0, v5
	v_max_f32_e32 v6, 0, v6
	v_max_f32_e32 v7, 0, v7
	v_pk_mul_f32 v[4:5], v[4:5], v[4:5]
	v_pk_mul_f32 v[6:7], v[6:7], v[6:7]
	v_cvt_pk_bf16_f32 v4, v4, v5
	v_cvt_pk_bf16_f32 v5, v6, v7
	ds_write_b64 v136, v[4:5] offset:25600
	v_mul_f32_e32 v0, v0, v214
	v_mul_f32_e32 v1, v1, v214
	v_mul_f32_e32 v2, v2, v214
	v_mul_f32_e32 v3, v3, v214
	v_max_f32_e32 v0, 0, v0
	v_max_f32_e32 v1, 0, v1
	v_max_f32_e32 v2, 0, v2
	v_max_f32_e32 v3, 0, v3
	v_pk_mul_f32 v[0:1], v[0:1], v[0:1]
	v_pk_mul_f32 v[2:3], v[2:3], v[2:3]
	v_cvt_pk_bf16_f32 v0, v0, v1
	v_cvt_pk_bf16_f32 v1, v2, v3
	ds_write_b64 v136, v[0:1] offset:25632
	s_waitcnt lgkmcnt(0)
	s_barrier
	v_and_b32_e32 v137, 63, v142
	v_lshrrev_b32_e32 v138, 5, v137
	v_and_b32_e32 v137, 31, v137
	s_lshl_b32 s79, s89, 5
	v_add_u32_e32 v138, s79, v138
	v_mul_u32_u24_e32 v139, 528, v138
	v_lshl_add_u32 v139, v137, 4, v139
	v_add_u32_e32 v139, 32, v139
	v_add_u32_e32 v140, s46, v138
	v_lshlrev_b32_e32 v140, 13, v140
	v_lshl_add_u32 v140, v137, 4, v140
	s_lshl_b32 s79, s48, 9
	v_add_u32_e32 v140, s79, v140
	ds_read_b128 v[0:3], v139 offset:0
	ds_read_b128 v[4:7], v139 offset:1056
	ds_read_b128 v[8:11], v139 offset:2112
	ds_read_b128 v[12:15], v139 offset:3168
	ds_read_b128 v[16:19], v139 offset:4224
	ds_read_b128 v[20:23], v139 offset:5280
	ds_read_b128 v[24:27], v139 offset:6336
	ds_read_b128 v[28:31], v139 offset:7392
	ds_read_b128 v[32:35], v139 offset:8448
	ds_read_b128 v[36:39], v139 offset:9504
	ds_read_b128 v[40:43], v139 offset:10560
	ds_read_b128 v[44:47], v139 offset:11616
	ds_read_b128 v[48:51], v139 offset:12672
	ds_read_b128 v[52:55], v139 offset:13728
	ds_read_b128 v[56:59], v139 offset:14784
	ds_read_b128 v[60:63], v139 offset:15840
	v_add_u32_e32 v217, 0x4000, v140
	v_add_u32_e32 v218, 0x8000, v140
	v_add_u32_e32 v219, 0xc000, v140
	v_add_u32_e32 v220, 0x10000, v140
	v_add_u32_e32 v221, 0x14000, v140
	v_add_u32_e32 v222, 0x18000, v140
	v_add_u32_e32 v223, 0x1c000, v140
	v_add_u32_e32 v224, 0x20000, v140
	v_add_u32_e32 v225, 0x24000, v140
	v_add_u32_e32 v226, 0x28000, v140
	v_add_u32_e32 v227, 0x2c000, v140
	v_add_u32_e32 v228, 0x30000, v140
	v_add_u32_e32 v229, 0x34000, v140
	v_add_u32_e32 v230, 0x38000, v140
	v_add_u32_e32 v231, 0x3c000, v140
	s_cmpk_lt_i32 s88, 0x800
	s_cbranch_scc0 .Lmy_hn_nocomp
	s_waitcnt vmcnt(0)
	v_and_b32_e32 v184, 0xff, v142
	v_lshl_add_u32 v184, v184, 2, 32
	v_add_u32_e32 v184, 0x213e0, v184
	v_add_f32_e32 v185, v168, v169
	v_add_f32_e32 v185, v185, v170
	v_add_f32_e32 v185, v185, v171
	v_add_f32_e32 v185, v185, v172
	v_add_f32_e32 v185, v185, v173
	v_add_f32_e32 v185, v185, v174
	v_add_f32_e32 v185, v185, v175
	v_add_f32_e32 v185, v185, v176
	v_add_f32_e32 v185, v185, v177
	v_add_f32_e32 v185, v185, v178
	v_add_f32_e32 v185, v185, v179
	v_add_f32_e32 v185, v185, v180
	v_add_f32_e32 v185, v185, v181
	v_add_f32_e32 v185, v185, v182
	v_add_f32_e32 v185, v185, v183
	v_fmamk_f32 v185, v185, 0x3a800000, v143
	v_mul_f32_e32 v186, 0x4b800000, v185
	v_cmp_gt_f32_e32 vcc, s66, v185
	s_nop 1
	v_cndmask_b32_e32 v185, v185, v186, vcc
	v_rsq_f32_e32 v185, v185
	s_nop 0
	v_mul_f32_e32 v186, 0x45800000, v185
	v_cndmask_b32_e32 v185, v185, v186, vcc
